# v30: v25 + write-through (sc1) stores for the layer-0 bf16 activation copy made in the prologue phase
# speedup vs baseline: 1.0040x; 1.0040x over previous
; __device__ __forceinline__ unsigned pk2(float lo, float hi) { return f2bf(lo) | (f2bf(hi) << 16); }
; __device__ __forceinline__ void phase_prologue(PtrTab TB, unsigned char* ws, float* xout, int l, LAS unsigned char* lds, int gw, int NGW, int lane, int wave) {
;     ...
;             for (int q = 0; q < 4; ++q) { const int r = r0 + q * NGW; if (r < M) { unsigned long long* o8 = (unsigned long long*)(xb + (size_t)r * D) + lane;
;                     if (lane < 4) ss[(size_t)r * 4 + lane] = lane == 0 ? s[q] : 0.f;
; #pragma unroll
;                     for (int j = 0; j < 4; ++j) { o8[64 * j] = (unsigned long long)pk2(v[q][j].x, v[q][j].y) | ((unsigned long long)pk2(v[q][j].z, v[q][j].w) << 32); } } }
.LBB0_232:
	s_or_b64 exec, exec, s[6:7]
	v_bfe_u32 v89, v60, 16, 1
	v_add3_u32 v60, v60, v89, s53
	v_bfe_u32 v89, v61, 16, 1
	v_lshrrev_b32_e32 v60, 16, v60
	v_add3_u32 v61, v61, v89, s53
	v_and_or_b32 v60, v61, s33, v60
	v_bfe_u32 v61, v62, 16, 1
	v_add3_u32 v61, v62, v61, s53
	v_bfe_u32 v62, v63, 16, 1
	s_waitcnt lgkmcnt(3)
	v_lshl_add_u64 v[90:91], s[82:83], 0, v[74:75]
	v_lshrrev_b32_e32 v61, 16, v61
	v_add3_u32 v62, v63, v62, s53
	s_mov_b32 s1, 0x4600000
	v_and_or_b32 v61, v62, s33, v61
	v_add_co_u32_e32 v62, vcc, s1, v90
	s_nop 1
	v_addc_co_u32_e32 v63, vcc, 0, v91, vcc
	global_store_dwordx2 v[62:63], v[60:61], off sc1
	v_bfe_u32 v60, v56, 16, 1
	v_add3_u32 v56, v56, v60, s53
	v_bfe_u32 v60, v57, 16, 1
	v_lshrrev_b32_e32 v56, 16, v56
	v_add3_u32 v57, v57, v60, s53
	v_and_or_b32 v56, v57, s33, v56
	v_bfe_u32 v57, v58, 16, 1
	v_add3_u32 v57, v58, v57, s53
	v_bfe_u32 v58, v59, 16, 1
	v_lshrrev_b32_e32 v57, 16, v57
	v_add3_u32 v58, v59, v58, s53
	v_and_or_b32 v57, v58, s33, v57
	global_store_dwordx2 v[62:63], v[56:57], off offset:512 sc1
	v_bfe_u32 v56, v52, 16, 1
	v_add3_u32 v52, v52, v56, s53
	v_bfe_u32 v56, v53, 16, 1
	v_lshrrev_b32_e32 v52, 16, v52
	v_add3_u32 v53, v53, v56, s53
	v_and_or_b32 v52, v53, s33, v52
	v_bfe_u32 v53, v54, 16, 1
	v_add3_u32 v53, v54, v53, s53
	v_bfe_u32 v54, v55, 16, 1
	v_lshrrev_b32_e32 v53, 16, v53
	v_add3_u32 v54, v55, v54, s53
	v_and_or_b32 v53, v54, s33, v53
	global_store_dwordx2 v[62:63], v[52:53], off offset:1024 sc1
	v_bfe_u32 v52, v48, 16, 1
	v_add3_u32 v48, v48, v52, s53
	v_bfe_u32 v52, v49, 16, 1
	v_lshrrev_b32_e32 v48, 16, v48
	v_add3_u32 v49, v49, v52, s53
	v_and_or_b32 v48, v49, s33, v48
	v_bfe_u32 v49, v50, 16, 1
	v_add3_u32 v49, v50, v49, s53
	v_bfe_u32 v50, v51, 16, 1
	v_lshrrev_b32_e32 v49, 16, v49
	v_add3_u32 v50, v51, v50, s53
	v_and_or_b32 v49, v50, s33, v49
	s_andn2_b64 vcc, exec, s[60:61]
	global_store_dwordx2 v[62:63], v[48:49], off offset:1536 sc1
	s_cbranch_vccz .LBB0_235
	s_andn2_b64 vcc, exec, s[38:39]
	s_cbranch_vccz .LBB0_238

; __device__ __forceinline__ unsigned pk2(float lo, float hi) { return f2bf(lo) | (f2bf(hi) << 16); }
; __device__ __forceinline__ void phase_prologue(PtrTab TB, unsigned char* ws, float* xout, int l, LAS unsigned char* lds, int gw, int NGW, int lane, int wave) {
;     ...
;             for (int q = 0; q < 4; ++q) { const int r = r0 + q * NGW; if (r < M) { unsigned long long* o8 = (unsigned long long*)(xb + (size_t)r * D) + lane;
;                     if (lane < 4) ss[(size_t)r * 4 + lane] = lane == 0 ? s[q] : 0.f;
; #pragma unroll
;                     for (int j = 0; j < 4; ++j) { o8[64 * j] = (unsigned long long)pk2(v[q][j].x, v[q][j].y) | ((unsigned long long)pk2(v[q][j].z, v[q][j].w) << 32); } } }
.LBB0_237:
	s_or_b64 exec, exec, s[6:7]
	v_bfe_u32 v50, v44, 16, 1
	v_add3_u32 v44, v44, v50, s53
	v_bfe_u32 v50, v45, 16, 1
	v_lshrrev_b32_e32 v44, 16, v44
	v_add3_u32 v45, v45, v50, s53
	v_and_or_b32 v44, v45, s33, v44
	v_bfe_u32 v45, v46, 16, 1
	v_add3_u32 v45, v46, v45, s53
	v_bfe_u32 v46, v47, 16, 1
	s_lshl_b64 s[6:7], s[44:45], 11
	v_lshrrev_b32_e32 v45, 16, v45
	v_add3_u32 v46, v47, v46, s53
	v_lshl_add_u64 v[48:49], v[68:69], 0, s[6:7]
	v_and_or_b32 v45, v46, s33, v45
	global_store_dwordx2 v[48:49], v[44:45], off sc1
	v_bfe_u32 v44, v40, 16, 1
	v_add3_u32 v40, v40, v44, s53
	v_bfe_u32 v44, v41, 16, 1
	v_lshrrev_b32_e32 v40, 16, v40
	v_add3_u32 v41, v41, v44, s53
	v_and_or_b32 v40, v41, s33, v40
	v_bfe_u32 v41, v42, 16, 1
	v_add3_u32 v41, v42, v41, s53
	v_bfe_u32 v42, v43, 16, 1
	v_lshrrev_b32_e32 v41, 16, v41
	v_add3_u32 v42, v43, v42, s53
	v_and_or_b32 v41, v42, s33, v41
	global_store_dwordx2 v[48:49], v[40:41], off offset:512 sc1
	v_bfe_u32 v40, v36, 16, 1
	v_add3_u32 v36, v36, v40, s53
	v_bfe_u32 v40, v37, 16, 1
	v_lshrrev_b32_e32 v36, 16, v36
	v_add3_u32 v37, v37, v40, s53
	v_and_or_b32 v36, v37, s33, v36
	v_bfe_u32 v37, v38, 16, 1
	v_add3_u32 v37, v38, v37, s53
	v_bfe_u32 v38, v39, 16, 1
	v_lshrrev_b32_e32 v37, 16, v37
	v_add3_u32 v38, v39, v38, s53
	v_and_or_b32 v37, v38, s33, v37
	global_store_dwordx2 v[48:49], v[36:37], off offset:1024 sc1
	v_bfe_u32 v36, v32, 16, 1
	v_add3_u32 v32, v32, v36, s53
	v_bfe_u32 v36, v33, 16, 1
	v_lshrrev_b32_e32 v32, 16, v32
	v_add3_u32 v33, v33, v36, s53
	v_and_or_b32 v32, v33, s33, v32
	v_bfe_u32 v33, v34, 16, 1
	v_add3_u32 v33, v34, v33, s53
	v_bfe_u32 v34, v35, 16, 1
	v_lshrrev_b32_e32 v33, 16, v33
	v_add3_u32 v34, v35, v34, s53
	v_and_or_b32 v33, v34, s33, v33
	global_store_dwordx2 v[48:49], v[32:33], off offset:1536 sc1
	s_andn2_b64 vcc, exec, s[38:39]
	s_cbranch_vccnz .LBB0_234

; __device__ __forceinline__ unsigned pk2(float lo, float hi) { return f2bf(lo) | (f2bf(hi) << 16); }
; __device__ __forceinline__ void phase_prologue(PtrTab TB, unsigned char* ws, float* xout, int l, LAS unsigned char* lds, int gw, int NGW, int lane, int wave) {
;     ...
;             for (int q = 0; q < 4; ++q) { const int r = r0 + q * NGW; if (r < M) { unsigned long long* o8 = (unsigned long long*)(xb + (size_t)r * D) + lane;
;                     if (lane < 4) ss[(size_t)r * 4 + lane] = lane == 0 ? s[q] : 0.f;
; #pragma unroll
;                     for (int j = 0; j < 4; ++j) { o8[64 * j] = (unsigned long long)pk2(v[q][j].x, v[q][j].y) | ((unsigned long long)pk2(v[q][j].z, v[q][j].w) << 32); } } }
.LBB0_240:
	s_or_b64 exec, exec, s[6:7]
	v_bfe_u32 v34, v28, 16, 1
	v_add3_u32 v28, v28, v34, s53
	v_bfe_u32 v34, v29, 16, 1
	v_lshrrev_b32_e32 v28, 16, v28
	v_add3_u32 v29, v29, v34, s53
	v_and_or_b32 v28, v29, s33, v28
	v_bfe_u32 v29, v30, 16, 1
	v_add3_u32 v29, v30, v29, s53
	v_bfe_u32 v30, v31, 16, 1
	s_lshl_b64 s[6:7], s[30:31], 11
	v_lshrrev_b32_e32 v29, 16, v29
	v_add3_u32 v30, v31, v30, s53
	v_lshl_add_u64 v[32:33], v[68:69], 0, s[6:7]
	v_and_or_b32 v29, v30, s33, v29
	global_store_dwordx2 v[32:33], v[28:29], off sc1
	v_bfe_u32 v28, v24, 16, 1
	v_add3_u32 v24, v24, v28, s53
	v_bfe_u32 v28, v25, 16, 1
	v_lshrrev_b32_e32 v24, 16, v24
	v_add3_u32 v25, v25, v28, s53
	v_and_or_b32 v24, v25, s33, v24
	v_bfe_u32 v25, v26, 16, 1
	v_add3_u32 v25, v26, v25, s53
	v_bfe_u32 v26, v27, 16, 1
	v_lshrrev_b32_e32 v25, 16, v25
	v_add3_u32 v26, v27, v26, s53
	v_and_or_b32 v25, v26, s33, v25
	global_store_dwordx2 v[32:33], v[24:25], off offset:512 sc1
	v_bfe_u32 v24, v16, 16, 1
	v_add3_u32 v16, v16, v24, s53
	v_bfe_u32 v24, v17, 16, 1
	v_lshrrev_b32_e32 v16, 16, v16
	v_add3_u32 v17, v17, v24, s53
	v_and_or_b32 v16, v17, s33, v16
	v_bfe_u32 v17, v18, 16, 1
	v_add3_u32 v17, v18, v17, s53
	v_bfe_u32 v18, v19, 16, 1
	v_lshrrev_b32_e32 v17, 16, v17
	v_add3_u32 v18, v19, v18, s53
	v_and_or_b32 v17, v18, s33, v17
	global_store_dwordx2 v[32:33], v[16:17], off offset:1024 sc1
	v_bfe_u32 v16, v20, 16, 1
	v_add3_u32 v16, v20, v16, s53
	v_bfe_u32 v17, v21, 16, 1
	v_lshrrev_b32_e32 v16, 16, v16
	v_add3_u32 v17, v21, v17, s53
	v_and_or_b32 v16, v17, s33, v16
	v_bfe_u32 v17, v22, 16, 1
	v_add3_u32 v17, v22, v17, s53
	v_bfe_u32 v18, v23, 16, 1
	v_lshrrev_b32_e32 v17, 16, v17
	v_add3_u32 v18, v23, v18, s53
	v_and_or_b32 v17, v18, s33, v17
	global_store_dwordx2 v[32:33], v[16:17], off offset:1536 sc1
	s_andn2_b64 vcc, exec, s[20:21]
	s_cbranch_vccnz .LBB0_229
